# plus RG-LRU unit prologue: the 16 gate-weight loads issued together with counted waits; weight-conversion loop waits only for the item it consumes
# speedup vs baseline: 1.0034x; 1.0034x over previous
; #define GAS __attribute__((address_space(1)))
; #define LAS __attribute__((address_space(3)))
; __device__ __forceinline__ void cvt_load(const CvtItem& c, int lane, f32x4 (&v)[8]) {
; #pragma unroll
;     for (int i = 0; i < 8; ++i) { const int kk = 4 * i + (lane >> 4); v[i] = *(const GAS f32x4*)(c.src + (size_t)kk * c.N + 4 * (lane & 15)); }
; }
; template <class Map> __device__ __forceinline__ void cvt_run(const Args& a, LAS float* scr, int count, int wk, int nw, int lane, Map map) {
;     if (wk >= count) return;
;     CvtItem cur = cvt_decode(a, map(wk)); f32x4 v[8]; cvt_load(cur, lane, v);
;     for (int it = wk; it < count; it += nw) {
;         const int nx = it + nw; CvtItem nxt = cur; f32x4 vn[8];
;         if (nx < count) { nxt = cvt_decode(a, map(nx)); cvt_load(nxt, lane, vn); }
;         cvt_store(cur, v, scr, lane);
;         cur = nxt;
; #pragma unroll
;         for (int i = 0; i < 8; ++i) v[i] = vn[i];
;     }
.LBB0_520:
	v_ashrrev_i32_e32 v68, 4, v125
	v_ashrrev_i32_e32 v17, 31, v68
	v_add_u32_e32 v70, 4, v68
	v_ashrrev_i32_e32 v67, 31, v70
	v_mul_lo_u32 v1, s36, v17
	v_mul_lo_u32 v4, s37, v68
	v_mad_u64_u32 v[2:3], s[38:39], s36, v68, 0
	v_lshlrev_b32_e32 v0, 2, v125
	v_add3_u32 v3, v3, v1, v4
	v_mul_lo_u32 v1, s36, v67
	v_mul_lo_u32 v8, s37, v70
	v_mad_u64_u32 v[6:7], s[38:39], s36, v70, 0
	v_and_b32_e32 v0, 60, v0
	v_add3_u32 v7, v7, v1, v8
	v_add_u32_e32 v72, 8, v68
	v_lshl_add_u64 v[2:3], v[2:3], 2, s[22:23]
	v_lshlrev_b32_e32 v4, 2, v0
	v_mov_b32_e32 v5, v16
	v_lshl_add_u64 v[6:7], v[6:7], 2, s[22:23]
	v_ashrrev_i32_e32 v69, 31, v72
	v_add_u32_e32 v76, 12, v68
	v_lshl_add_u64 v[2:3], v[2:3], 0, v[4:5]
	v_lshl_add_u64 v[6:7], v[6:7], 0, v[4:5]
	v_ashrrev_i32_e32 v71, 31, v76
	global_load_dwordx4 v[34:37], v[2:3], off nt
	global_load_dwordx4 v[38:41], v[6:7], off nt
	v_mul_lo_u32 v1, s36, v69
	v_mul_lo_u32 v6, s37, v72
	v_mad_u64_u32 v[2:3], s[38:39], s36, v72, 0
	v_add3_u32 v3, v3, v1, v6
	v_mul_lo_u32 v1, s36, v71
	v_mul_lo_u32 v8, s37, v76
	v_mad_u64_u32 v[6:7], s[38:39], s36, v76, 0
	v_add3_u32 v7, v7, v1, v8
	v_add_u32_e32 v78, 16, v68
	v_lshl_add_u64 v[2:3], v[2:3], 2, s[22:23]
	v_lshl_add_u64 v[6:7], v[6:7], 2, s[22:23]
	v_ashrrev_i32_e32 v73, 31, v78
	v_add_u32_e32 v80, 20, v68
	v_lshl_add_u64 v[2:3], v[2:3], 0, v[4:5]
	v_lshl_add_u64 v[6:7], v[6:7], 0, v[4:5]
	v_ashrrev_i32_e32 v75, 31, v80
	global_load_dwordx4 v[42:45], v[2:3], off nt
	global_load_dwordx4 v[46:49], v[6:7], off nt
	v_mul_lo_u32 v1, s36, v73
	v_mul_lo_u32 v6, s37, v78
	v_mad_u64_u32 v[2:3], s[38:39], s36, v78, 0
	v_add3_u32 v3, v3, v1, v6
	v_mul_lo_u32 v1, s36, v75
	v_mul_lo_u32 v8, s37, v80
	v_mad_u64_u32 v[6:7], s[38:39], s36, v80, 0
	v_add3_u32 v7, v7, v1, v8
	v_add_u32_e32 v82, 24, v68
	v_lshl_add_u64 v[2:3], v[2:3], 2, s[22:23]
	v_lshl_add_u64 v[6:7], v[6:7], 2, s[22:23]
	v_ashrrev_i32_e32 v77, 31, v82
	v_add_u32_e32 v84, 28, v68
	v_lshl_add_u64 v[2:3], v[2:3], 0, v[4:5]
	v_lshl_add_u64 v[6:7], v[6:7], 0, v[4:5]
	v_ashrrev_i32_e32 v79, 31, v84
	global_load_dwordx4 v[50:53], v[2:3], off nt
	global_load_dwordx4 v[54:57], v[6:7], off nt
	v_mul_lo_u32 v1, s36, v77
	v_mul_lo_u32 v6, s37, v82
	v_mad_u64_u32 v[2:3], s[38:39], s36, v82, 0
	v_add3_u32 v3, v3, v1, v6
	v_mul_lo_u32 v1, s36, v79
	v_mul_lo_u32 v8, s37, v84
	v_mad_u64_u32 v[6:7], s[36:37], s36, v84, 0
	v_lshl_add_u64 v[2:3], v[2:3], 2, s[22:23]
	v_add3_u32 v7, v7, v1, v8
	v_lshl_add_u64 v[2:3], v[2:3], 0, v[4:5]
	v_lshl_add_u64 v[6:7], v[6:7], 2, s[22:23]
	v_lshl_add_u64 v[6:7], v[6:7], 0, v[4:5]
	global_load_dwordx4 v[58:61], v[2:3], off nt
	global_load_dwordx4 v[62:65], v[6:7], off nt
	s_mul_i32 s4, s2, 0x2100
	s_add_i32 s4, s4, 0
	v_lshlrev_b32_e32 v2, 4, v125
	s_movk_i32 s21, 0x104
	v_and_b32_e32 v86, 16, v2
	v_mov_b32_e32 v5, s4
	v_ashrrev_i32_e32 v2, 1, v125
	v_mad_u32_u24 v6, v86, s21, v5
	v_ashrrev_i32_e32 v3, 31, v2
	v_lshl_add_u32 v81, v2, 2, v6
	v_lshlrev_b64 v[88:89], 10, v[2:3]
	v_lshlrev_b32_e32 v2, 3, v125
	v_and_b32_e32 v2, 24, v2
	v_mad_u32_u24 v5, v2, s21, v5
	v_lshlrev_b32_e32 v90, 1, v2
	v_ashrrev_i32_e32 v2, 2, v125
	v_and_b32_e32 v3, -4, v125
	v_add_u32_e32 v7, 64, v125
	v_add_u32_e32 v100, v5, v3
	v_ashrrev_i32_e32 v3, 31, v2
	v_lshlrev_b64 v[92:93], 11, v[2:3]
	v_ashrrev_i32_e32 v2, 2, v7
	v_and_b32_e32 v3, -4, v7
	v_add_u32_e32 v101, v5, v3
	v_ashrrev_i32_e32 v3, 31, v2
	v_lshlrev_b64 v[94:95], 11, v[2:3]
	v_add_u32_e32 v3, 0x80, v125
	v_ashrrev_i32_e32 v2, 2, v3
	v_and_b32_e32 v3, -4, v3
	v_add_u32_e32 v102, v5, v3
	v_ashrrev_i32_e32 v3, 31, v2
	v_lshlrev_b64 v[96:97], 11, v[2:3]
	v_add_u32_e32 v2, 0xc0, v125
	v_add_u32_e32 v1, s4, v4
	v_mul_lo_u32 v4, v68, s21
	v_ashrrev_i32_e32 v83, 1, v7
	v_ashrrev_i32_e32 v103, 2, v2
	v_and_b32_e32 v2, -4, v2
	s_lshl_b32 s4, s2, 5
	v_mov_b32_e32 v87, v16
	v_lshl_add_u32 v85, v83, 2, v6
	v_mov_b32_e32 v91, v16
	v_add_u32_e32 v104, v5, v2
	s_addk_i32 s4, 0x100
	v_lshlrev_b32_e32 v98, 2, v0
	v_add_u32_e32 v105, v1, v4
	s_mov_b32 s21, s2
	v_mov_b32_e32 v106, v74
	s_mov_b64 s[36:37], s[8:9]
	s_mov_b32 s25, s34
	s_waitcnt vmcnt(0)
	s_branch .LBB0_522
.LBB0_521:
	v_ashrrev_i32_e32 v39, 31, v38
	v_lshlrev_b64 v[38:39], s38, v[38:39]
	v_lshl_add_u64 v[38:39], s[8:9], 0, v[38:39]
	v_lshl_add_u64 v[38:39], v[38:39], 0, v[40:41]
	global_store_dwordx4 v[38:39], v[34:37], off
	s_waitcnt lgkmcnt(0)
	s_add_i32 s21, s21, 8
	s_addk_i32 s4, 0x100
	s_and_b64 vcc, exec, s[22:23]
	s_mov_b64 s[8:9], s[36:37]
	s_mov_b32 s34, s25
	v_mov_b32_e32 v74, v106
	s_waitcnt vmcnt(2)
	v_mov_b32_e32 v34, v4
	v_mov_b32_e32 v35, v5
	v_mov_b32_e32 v36, v6
	v_mov_b32_e32 v37, v7
	v_mov_b32_e32 v38, v0
	v_mov_b32_e32 v39, v1
	v_mov_b32_e32 v40, v2
	v_mov_b32_e32 v41, v3
	v_mov_b32_e32 v42, v12
	v_mov_b32_e32 v43, v13
	v_mov_b32_e32 v44, v14
	v_mov_b32_e32 v45, v15
	v_mov_b32_e32 v46, v8
	v_mov_b32_e32 v47, v9
	v_mov_b32_e32 v48, v10
	v_mov_b32_e32 v49, v11
	v_mov_b32_e32 v50, v22
	v_mov_b32_e32 v51, v23
	v_mov_b32_e32 v52, v24
	v_mov_b32_e32 v53, v25
	v_mov_b32_e32 v54, v18
	v_mov_b32_e32 v55, v19
	v_mov_b32_e32 v56, v20
	v_mov_b32_e32 v57, v21
	v_mov_b32_e32 v58, v30
	v_mov_b32_e32 v59, v31
	v_mov_b32_e32 v60, v32
	v_mov_b32_e32 v61, v33
	v_mov_b32_e32 v62, v26
	v_mov_b32_e32 v63, v27
	v_mov_b32_e32 v64, v28
	v_mov_b32_e32 v65, v29
	s_cbranch_vccnz .LBB0_541

; __device__ __forceinline__ unsigned pk4_fp8(float a, float b, float c, float d) { int w = 0; w = __builtin_amdgcn_cvt_pk_fp8_f32(a, b, w, false); w = __builtin_amdgcn_cvt_pk_fp8_f32(c, d, w, true); return (unsigned)w; }
; #define GAS __attribute__((address_space(1)))
; #define LAS __attribute__((address_space(3)))
; #define LDS_WAIT() asm volatile("s_waitcnt lgkmcnt(0)" ::: "memory")
; __device__ __forceinline__ unsigned pk4_fp8(float a, float b, float c, float d) { int w = 0; w = __builtin_amdgcn_cvt_pk_fp8_f32(a, b, w, false); w = __builtin_amdgcn_cvt_pk_fp8_f32(c, d, w, true); return (unsigned)w; }
; __device__ __forceinline__ void cvt_store(const CvtItem& c, const f32x4 (&v)[8], LAS float* scr, int lane) {
; #pragma unroll
;     for (int i = 0; i < 8; ++i) { const int kk = 4 * i + (lane >> 4); LAS float* p = scr + kk * 65 + 4 * (lane & 15); p[0] = v[i][0]; p[1] = v[i][1]; p[2] = v[i][2]; p[3] = v[i][3]; }
;     LDS_WAIT(); asm volatile("" ::: "memory");
;     if (c.f8) {
; #pragma unroll
;         for (int j = 0; j < 2; ++j) { const int idx = lane + 64 * j, n = idx >> 1, cc = idx & 1; const LAS float* s = scr + (16 * cc) * 65 + n;
;             v4u o; o.x = pk4_fp8(s[0 * 65] * F8_SW, s[1 * 65] * F8_SW, s[2 * 65] * F8_SW, s[3 * 65] * F8_SW); o.y = pk4_fp8(s[4 * 65] * F8_SW, s[5 * 65] * F8_SW, s[6 * 65] * F8_SW, s[7 * 65] * F8_SW);
;             o.z = pk4_fp8(s[8 * 65] * F8_SW, s[9 * 65] * F8_SW, s[10 * 65] * F8_SW, s[11 * 65] * F8_SW); o.w = pk4_fp8(s[12 * 65] * F8_SW, s[13 * 65] * F8_SW, s[14 * 65] * F8_SW, s[15 * 65] * F8_SW);
;             *(GAS v4u*)(c.dst + (size_t)n * D + 16 * cc) = o; }
.LBB0_536:
	ds_write2_b32 v105, v34, v35 offset1:1
	ds_write2_b32 v105, v36, v37 offset0:2 offset1:3
	v_add_u32_e32 v34, 0x410, v105
	ds_write2_b32 v34, v38, v39 offset1:1
	v_add_u32_e32 v34, 0x418, v105
	ds_write2_b32 v34, v40, v41 offset1:1
	v_add_u32_e32 v34, 0x820, v105
	ds_write2_b32 v34, v42, v43 offset1:1
	v_add_u32_e32 v34, 0x828, v105
	ds_write2_b32 v34, v44, v45 offset1:1
	v_add_u32_e32 v34, 0xc30, v105
	ds_write2_b32 v34, v46, v47 offset1:1
	v_add_u32_e32 v34, 0xc38, v105
	ds_write2_b32 v34, v48, v49 offset1:1
	v_add_u32_e32 v34, 0x1040, v105
	ds_write2_b32 v34, v50, v51 offset1:1
	v_add_u32_e32 v34, 0x1048, v105
	ds_write2_b32 v34, v52, v53 offset1:1
	v_add_u32_e32 v34, 0x1450, v105
	ds_write2_b32 v34, v54, v55 offset1:1
	v_add_u32_e32 v34, 0x1458, v105
	ds_write2_b32 v34, v56, v57 offset1:1
	v_add_u32_e32 v34, 0x1860, v105
	ds_write2_b32 v34, v58, v59 offset1:1
	v_add_u32_e32 v34, 0x1868, v105
	ds_write2_b32 v34, v60, v61 offset1:1
	v_add_u32_e32 v34, 0x1c70, v105
	ds_write2_b32 v34, v62, v63 offset1:1
	v_add_u32_e32 v34, 0x1c78, v105
	ds_write2_b32 v34, v64, v65 offset1:1
	s_waitcnt lgkmcnt(0)
	s_cmp_eq_u32 s34, 0
	s_cbranch_scc1 .LBB0_538
	ds_read2_b32 v[34:35], v81 offset1:65
	s_mov_b64 s[42:43], 0
	s_waitcnt lgkmcnt(0)
	v_mul_f32_e32 v36, 0x42800000, v34
	v_mul_f32_e32 v37, 0x42800000, v35
	ds_read2_b32 v[34:35], v81 offset0:130 offset1:195
	s_waitcnt lgkmcnt(0)
	v_mul_f32_e32 v38, 0x42800000, v34
	v_mov_b32_e32 v34, v16
	v_cvt_pk_fp8_f32 v34, v36, v37
	v_mul_f32_e32 v35, 0x42800000, v35
	v_cvt_pk_fp8_f32 v34, v38, v35 op_sel:[0,0,1]
	v_add_u32_e32 v35, 0x400, v81
	ds_read2_b32 v[36:37], v35 offset0:4 offset1:69
	s_waitcnt lgkmcnt(0)
	v_mul_f32_e32 v38, 0x42800000, v36
	v_mul_f32_e32 v39, 0x42800000, v37
	ds_read2_b32 v[36:37], v35 offset0:134 offset1:199
	v_mov_b32_e32 v35, v16
	v_cvt_pk_fp8_f32 v35, v38, v39
	v_add_u32_e32 v38, 0x800, v81
	s_waitcnt lgkmcnt(0)
	v_mul_f32_e32 v36, 0x42800000, v36
	v_mul_f32_e32 v37, 0x42800000, v37
	v_cvt_pk_fp8_f32 v35, v36, v37 op_sel:[0,0,1]
	ds_read2_b32 v[36:37], v38 offset0:8 offset1:73
	s_waitcnt lgkmcnt(0)
	v_mul_f32_e32 v39, 0x42800000, v36
	v_mul_f32_e32 v40, 0x42800000, v37
	ds_read2_b32 v[36:37], v38 offset0:138 offset1:203
	s_waitcnt lgkmcnt(0)
	v_mul_f32_e32 v38, 0x42800000, v36
	v_mov_b32_e32 v36, v16
	v_cvt_pk_fp8_f32 v36, v39, v40
	v_mul_f32_e32 v37, 0x42800000, v37
	v_cvt_pk_fp8_f32 v36, v38, v37 op_sel:[0,0,1]
	v_add_u32_e32 v37, 0xc00, v81
	ds_read2_b32 v[38:39], v37 offset0:12 offset1:77
	s_waitcnt lgkmcnt(0)
	v_mul_f32_e32 v40, 0x42800000, v38
	v_mul_f32_e32 v41, 0x42800000, v39
	ds_read2_b32 v[38:39], v37 offset0:142 offset1:207
	v_mov_b32_e32 v37, v16
	v_cvt_pk_fp8_f32 v37, v40, v41
	s_waitcnt lgkmcnt(0)
	v_mul_f32_e32 v38, 0x42800000, v38
	v_mul_f32_e32 v39, 0x42800000, v39
	v_cvt_pk_fp8_f32 v37, v38, v39 op_sel:[0,0,1]
	v_lshl_add_u64 v[38:39], s[8:9], 0, v[88:89]
	v_lshl_add_u64 v[38:39], v[38:39], 0, v[86:87]
	global_store_dwordx4 v[38:39], v[34:37], off
	ds_read2_b32 v[34:35], v85 offset1:65
	s_waitcnt lgkmcnt(0)
	v_mul_f32_e32 v36, 0x42800000, v34
	v_mul_f32_e32 v37, 0x42800000, v35
	ds_read2_b32 v[34:35], v85 offset0:130 offset1:195
	s_waitcnt lgkmcnt(0)
	v_mul_f32_e32 v38, 0x42800000, v34
	v_mov_b32_e32 v34, v16
	v_cvt_pk_fp8_f32 v34, v36, v37
	v_mul_f32_e32 v35, 0x42800000, v35
	v_cvt_pk_fp8_f32 v34, v38, v35 op_sel:[0,0,1]
	v_add_u32_e32 v35, 0x400, v85
	ds_read2_b32 v[36:37], v35 offset0:4 offset1:69
	s_waitcnt lgkmcnt(0)
	v_mul_f32_e32 v38, 0x42800000, v36
	v_mul_f32_e32 v39, 0x42800000, v37
	ds_read2_b32 v[36:37], v35 offset0:134 offset1:199
	v_mov_b32_e32 v35, v16
	v_cvt_pk_fp8_f32 v35, v38, v39
	v_add_u32_e32 v38, 0x800, v85
	s_waitcnt lgkmcnt(0)
	v_mul_f32_e32 v36, 0x42800000, v36
	v_mul_f32_e32 v37, 0x42800000, v37
	v_cvt_pk_fp8_f32 v35, v36, v37 op_sel:[0,0,1]
	ds_read2_b32 v[36:37], v38 offset0:8 offset1:73
	s_waitcnt lgkmcnt(0)
	v_mul_f32_e32 v39, 0x42800000, v36
	v_mul_f32_e32 v40, 0x42800000, v37
	ds_read2_b32 v[36:37], v38 offset0:138 offset1:203
	s_waitcnt lgkmcnt(0)
	v_mul_f32_e32 v38, 0x42800000, v36
	v_mov_b32_e32 v36, v16
	v_cvt_pk_fp8_f32 v36, v39, v40
	v_mul_f32_e32 v37, 0x42800000, v37
	v_cvt_pk_fp8_f32 v36, v38, v37 op_sel:[0,0,1]
	v_add_u32_e32 v37, 0xc00, v85
	ds_read2_b32 v[38:39], v37 offset0:12 offset1:77
	s_waitcnt lgkmcnt(0)
	v_mul_f32_e32 v40, 0x42800000, v38
	v_mul_f32_e32 v41, 0x42800000, v39
	ds_read2_b32 v[38:39], v37 offset0:142 offset1:207
	v_mov_b32_e32 v37, v16
	v_cvt_pk_fp8_f32 v37, v40, v41
	s_waitcnt lgkmcnt(0)
	v_mul_f32_e32 v38, 0x42800000, v38
	v_mul_f32_e32 v39, 0x42800000, v39
	v_cvt_pk_fp8_f32 v37, v38, v39 op_sel:[0,0,1]
	s_branch .LBB0_539

; __device__ __forceinline__ unsigned pk2(float lo, float hi) { typedef __bf16 bf2_t __attribute__((ext_vector_type(2))); const f32x2 v = {lo, hi}; return __builtin_bit_cast(unsigned, __builtin_convertvector(v, bf2_t)); }
; __device__ __forceinline__ void unit(LAS unsigned char* lds, const Args& a, int l, int tk, int wave, int lane, int tid) {
;     ...
;     {
; #pragma unroll
;       for (int ff = 0; ff < 2; ++ff) { const int f = 2 * wave + ff, gate = f >> 3, nt = (f >> 1) & 3, s = f & 1;
;         const float* W = (gate ? a.in[I_WX] : a.in[I_WA]) + ((size_t)l * 4 + blk) * 64 * 64;
;         const int k0 = 32 * s + 8 * fq, oc = 16 * nt + fr; v4u pa;
;         pa.x = pk2(W[(k0 + 0) * 64 + oc], W[(k0 + 1) * 64 + oc]); pa.y = pk2(W[(k0 + 2) * 64 + oc], W[(k0 + 3) * 64 + oc]); pa.z = pk2(W[(k0 + 4) * 64 + oc], W[(k0 + 5) * 64 + oc]); pa.w = pk2(W[(k0 + 6) * 64 + oc], W[(k0 + 7) * 64 + oc]);
;         WF[f * 64 + lane] = pa; } }
;     float ba[4], bx[4], csp[4], carry[4];
; #pragma unroll
;     for (int nt = 0; nt < 4; ++nt) { const int ch = l * LW + 64 * blk + 16 * nt + fr; ba[nt] = a.in[I_BA][ch]; bx[nt] = a.in[I_BX][ch]; csp[nt] = 8.0f * log1pf(expf(-a.in[I_LAM][ch])); carry[nt] = 0.f; }
.LBB0_543:
	s_andn2_b64 vcc, exec, s[8:9]
	s_cbranch_vccnz .LBB0_236
	s_sub_i32 s62, 0x7f, s62
	s_lshl_b32 s4, s2, 4
	s_lshl_b32 s9, s2, 11
	s_and_b32 s3, s62, 3
	v_ashrrev_i32_e32 v72, 4, v125
	s_and_b32 s8, s4, 48
	s_add_i32 s9, s9, 0
	v_readlane_b32 s36, v250, 0
	v_and_b32_e32 v17, 15, v125
	s_cmp_lt_u32 s2, 4
	v_lshlrev_b32_e32 v0, 9, v72
	v_readlane_b32 s38, v250, 2
	v_or3_b32 v6, s8, v0, v17
	v_lshl_add_u32 v0, v125, 4, s9
	v_readlane_b32 s39, v250, 3
	s_cselect_b32 s9, s94, s38
	v_readlane_b32 s22, v255, 6
	s_cselect_b32 s8, s95, s39
	v_readlane_b32 s23, v255, 7
	s_add_u32 s9, s9, s22
	s_addc_u32 s21, s8, s23
	s_lshl_b32 s8, s3, 14
	s_add_u32 s8, s9, s8
	s_addc_u32 s9, s21, 0
	v_ashrrev_i32_e32 v7, 31, v6
	v_lshl_add_u64 v[8:9], v[6:7], 2, s[8:9]
	v_add_u32_e32 v5, 0x16800, v0
	v_add_u32_e32 v0, 0x800, v6
	v_ashrrev_i32_e32 v1, 31, v0
	v_lshl_add_u64 v[6:7], v[0:1], 2, s[8:9]
	global_load_dword v144, v[8:9], off
	global_load_dword v145, v[8:9], off offset:256
	global_load_dword v146, v[8:9], off offset:512
	global_load_dword v147, v[8:9], off offset:768
	global_load_dword v148, v[8:9], off offset:1024
	global_load_dword v149, v[8:9], off offset:1280
	global_load_dword v150, v[8:9], off offset:1536
	global_load_dword v151, v[8:9], off offset:1792
	global_load_dword v152, v[6:7], off
	global_load_dword v153, v[6:7], off offset:256
	global_load_dword v154, v[6:7], off offset:512
	global_load_dword v155, v[6:7], off offset:768
	global_load_dword v156, v[6:7], off offset:1024
	global_load_dword v157, v[6:7], off offset:1280
	global_load_dword v158, v[6:7], off offset:1536
	global_load_dword v159, v[6:7], off offset:1792
	s_lshl_b32 s3, s3, 6
	v_readlane_b32 s37, v250, 1
	v_readlane_b32 s40, v250, 4
	v_readlane_b32 s41, v250, 5
	v_readlane_b32 s42, v250, 6
	v_readlane_b32 s43, v250, 7
	v_add_u32_e32 v4, s74, v125
	v_readlane_b32 s44, v250, 8
	v_readlane_b32 s45, v250, 9
	v_readlane_b32 s46, v250, 10
	v_readlane_b32 s47, v250, 11
	v_readlane_b32 s48, v250, 12
	v_readlane_b32 s49, v250, 13
	v_readlane_b32 s50, v250, 14
	v_readlane_b32 s51, v250, 15
	v_readlane_b32 s8, v255, 8
	s_or_b32 s21, s3, s8
	s_movk_i32 s8, 0x140
	v_cmp_gt_i32_e32 vcc, s8, v4
	s_waitcnt vmcnt(0)
	v_cvt_pk_bf16_f32 v0, v144, v145
	v_cvt_pk_bf16_f32 v1, v146, v147
	v_cvt_pk_bf16_f32 v2, v148, v149
	v_cvt_pk_bf16_f32 v3, v150, v151
	ds_write_b128 v5, v[0:3]
	v_cvt_pk_bf16_f32 v0, v152, v153
	v_cvt_pk_bf16_f32 v1, v154, v155
	v_cvt_pk_bf16_f32 v2, v156, v157
	v_cvt_pk_bf16_f32 v3, v158, v159
	ds_write_b128 v5, v[0:3] offset:1024
	v_or_b32_e32 v0, s21, v17
	v_mov_b32_e32 v1, v16
	v_lshlrev_b64 v[0:1], 2, v[0:1]
	v_lshl_add_u64 v[2:3], s[36:37], 0, v[0:1]
	v_lshl_add_u64 v[6:7], s[40:41], 0, v[0:1]
	v_lshl_add_u64 v[0:1], s[42:43], 0, v[0:1]
	global_load_dword v67, v[2:3], off
	global_load_dword v106, v[6:7], off
	global_load_dword v79, v[0:1], off
	global_load_dword v107, v[2:3], off offset:64
	global_load_dword v108, v[6:7], off offset:64
	global_load_dword v78, v[0:1], off offset:64
	global_load_dword v109, v[2:3], off offset:128
	global_load_dword v110, v[6:7], off offset:128
	global_load_dword v77, v[0:1], off offset:128
	global_load_dword v111, v[2:3], off offset:192
	global_load_dword v112, v[6:7], off offset:192
	global_load_dword v76, v[0:1], off offset:192
	s_and_saveexec_b64 s[8:9], vcc
	s_mov_b64 s[36:37], 0x1200
	s_cbranch_execz .LBB0_550
	v_ashrrev_i32_e32 v2, 6, v4
	v_and_b32_e32 v5, 63, v125
	v_cmp_lt_i32_e32 vcc, 3, v2
	s_and_saveexec_b64 s[22:23], vcc
	s_xor_b64 s[22:23], exec, s[22:23]
	v_or_b32_e32 v0, s21, v5
	v_mov_b32_e32 v1, v16
	v_lshl_add_u64 v[0:1], v[0:1], 2, s[92:93]
	s_andn2_saveexec_b64 s[22:23], s[22:23]
	s_cbranch_execz .LBB0_549
	v_ashrrev_i32_e32 v3, 31, v2
	v_readlane_b32 s34, v255, 9
	v_lshlrev_b64 v[0:1], 10, v[2:3]
	v_readlane_b32 s35, v255, 10
	v_lshlrev_b32_e32 v2, 2, v5
	v_mov_b32_e32 v3, v16
	v_lshl_add_u64 v[0:1], s[34:35], 0, v[0:1]
	v_readlane_b32 s34, v254, 39
	v_readlane_b32 s35, v254, 40
	s_lshl_b32 s34, s3, 2
	s_mov_b32 s21, s35
	v_writelane_b32 v254, s20, 39
	v_lshl_add_u64 v[0:1], v[0:1], 0, s[34:35]
	v_lshl_add_u64 v[0:1], v[0:1], 0, v[2:3]
	v_writelane_b32 v254, s21, 40
